# v21 + context rows of the pre-norm spread over all workgroups (everyone waits for the 64 context tiles after its latent share) + initial cooperative-groups grid sync dropped
# speedup vs baseline: 1.0097x; 1.0064x over previous
; #define LAS __attribute__((address_space(3)))
; #define GLOBAL_PTR(T, p) ((T*)(__attribute__((address_space(1))) T*)(launder_u64((unsigned long long)(p))))
; DI void prologue_a(Frame& F, const Args& AR, int ps_lo, int ps_hi) {
;     LAS float* scr = (LAS float*)(F.lds + F.wave * 16384);
;     LAS float* tw = (LAS float*)(F.lds + 131072);
;     if (F.tid < 64) { tw[F.tid] = cospif((float)F.tid * (1.0f / 32.0f)); tw[64 + F.tid] = sinpif((float)F.tid * (1.0f / 32.0f)); }
;     __syncthreads();
; __global__ void __launch_bounds__(512, 2) fwd_megakernel(Args args) {
;     ...
;     cg::grid_group grid = cg::this_grid();
;     Frame F;
;     F.lds = (LAS unsigned char*)lds_raw;
;     F.tid = threadIdx.x; F.lane = F.tid & 63; F.wave = __builtin_amdgcn_readfirstlane(F.tid >> 6);
;     F.G = gridDim.x; { const int bx = blockIdx.x; F.vcu = (F.G % 8 == 0) ? (bx % 8) * (F.G / 8) + bx / 8 : bx; }
;     F.out = GLOBAL_PTR(float, args.out); F.ws = GLOBAL_PTR(unsigned char, args.ws);
;     int bx = blockIdx.x;
;     const Args& AR = args;
;     unsigned* barw = GLOBAL_PTR(unsigned, args.ws); unsigned nbar = 0u;
;     grid.sync();
.LBB0_2:
	s_load_dwordx4 s[44:47], s[0:1], 0x98
	v_lshrrev_b32_e32 v1, 20, v0
	v_lshrrev_b32_e32 v0, 10, v0
	v_or_b32_e32 v0, v0, v1
	v_and_or_b32 v0, v0, s4, v163
	s_waitcnt lgkmcnt(0)
	s_mov_b64 s[8:9], s[46:47]
	v_cmp_eq_u32_e32 vcc, 0, v0
	s_barrier
	s_and_saveexec_b64 s[4:5], vcc
.LBB0_12:
	s_or_b64 exec, exec, s[4:5]
	v_cmp_gt_u32_e32 vcc, 64, v163
	s_barrier
	s_and_saveexec_b64 s[6:7], vcc
	s_cbranch_execz .LBB0_14
	v_cvt_f32_u32_e32 v0, v163
	s_mov_b32 s10, 0x7f800000
	v_mov_b32_e32 v4, 0xbf1f24be
	v_mul_f32_e32 v0, 0x3d000000, v0
	v_mul_f32_e32 v1, 0.5, v0
	v_fract_f32_e32 v2, v1
	v_add_f32_e32 v2, v2, v2
	v_cmp_neq_f32_e32 vcc, s10, v1
	s_nop 1
	v_cndmask_b32_e32 v1, 0, v2, vcc
	v_cmp_lt_f32_e32 vcc, 1.0, v0
	s_nop 1
	v_cndmask_b32_e32 v1, v0, v1, vcc
	v_add_f32_e32 v2, v1, v1
	v_rndne_f32_e32 v2, v2
	v_fmac_f32_e32 v1, -0.5, v2
	v_cvt_i32_f32_e32 v3, v2
	v_mul_f32_e32 v2, v1, v1
	v_fmac_f32_e32 v4, 0x3e75aa41, v2
	v_fmaak_f32 v4, v2, v4, 0x40234736
	v_fmaak_f32 v4, v2, v4, 0xc0a55e0e
	v_mul_f32_e32 v6, v1, v2
	v_mul_f32_e32 v4, v6, v4
	v_fmamk_f32 v1, v1, 0x40490fdb, v4
	v_mov_b32_e32 v4, 0x3e642e9d
	v_fmac_f32_e32 v4, 0x3d4be544, v2
	v_fmaak_f32 v4, v2, v4, 0xbfaad1da
	v_fmaak_f32 v4, v2, v4, 0x4081e0d3
	v_fmaak_f32 v4, v2, v4, 0xc09de9e6
	v_fma_f32 v2, v2, v4, 1.0
	v_and_b32_e32 v4, 1, v3
	v_and_b32_e32 v5, 2, v3
	v_cmp_eq_u32_e32 vcc, 0, v4
	v_cmp_eq_u32_e64 s[4:5], 0, v5
	v_mov_b32_e32 v5, 0x7fc00000
	v_cndmask_b32_e64 v4, -v1, v2, vcc
	v_cndmask_b32_e64 v4, -v4, v4, s[4:5]
	v_cmp_lg_f32_e64 s[4:5], s10, v0
	v_cndmask_b32_e32 v1, v2, v1, vcc
	v_lshlrev_b32_e32 v2, 30, v3
	s_brev_b32 s10, 1
	v_cndmask_b32_e64 v0, v5, v4, s[4:5]
	v_lshl_add_u32 v4, v163, 2, 0
	v_bitop3_b32 v1, v2, v1, s10 bitop3:0x6c
	v_add_u32_e32 v4, 0x20000, v4
	v_cndmask_b32_e64 v1, v5, v1, s[4:5]
	ds_write2st64_b32 v4, v0, v1 offset1:1

; DI const float* in_ptr(const Args& AR, int i) { asm volatile("" : "+s"(i)); return GLOBAL_PTR(const float, AR.in[i]); }
; DI void norm_phase(Frame& F, const float* srcL, const float* srcC, const float* g, const float* modl, int sub) {
;     const int gw = F.vcu * 8 + F.wave; constexpr int RPW = TT / 2048;
;     bf16_t* H = WSP(bf16_t, WS_H);
;     int cur_bi = -1; f32x4 gs[4], sh[4];
;     for (int row = gw * RPW; row < gw * RPW + RPW; ++row) {
;         const int bi = row < TL ? (row >> 12) : 16;
;         if (bi != cur_bi) { cur_bi = bi; const float* mp = modl + (size_t)bi * MODW + sub * 3072;
; #pragma unroll
;             for (int j = 0; j < 4; ++j) { const int k = (F.lane + 64 * j) * 4; const f32x4 gg = *(const f32x4*)(g + k), sc = *(const f32x4*)(mp + 1024 + k); sh[j] = *(const f32x4*)(mp + k); gs[j] = gg * (sc + 1.0f); } }
; __global__ void __launch_bounds__(512, 2) fwd_megakernel(Args args) {
;     ...
;             if (type == T_NORM) {
;                 const int sub = op == 0 ? 0 : (op == 3 ? 1 : 2);
;                 if (even && op == 3) norm_pair_phase(F, srcL, srcC, in_ptr(AR, 4) + (size_t)(l * 3 + sub) * DM, modl, sub);
;                 else norm_phase(F, srcL, srcC, in_ptr(AR, 4) + (size_t)(l * 3 + sub) * DM, modl, sub);
.LBB0_522:
	s_andn2_b64 vcc, exec, s[4:5]
	s_cbranch_vccnz .LBB0_578
	s_cmp_lg_u32 s35, 1
	s_cbranch_scc1 .LBB0_578
	s_cmp_eq_u32 s44, 3
	v_readlane_b32 s6, v255, 17
	s_cselect_b64 s[4:5], -1, 0
	v_readlane_b32 s7, v255, 18
	s_and_b64 s[6:7], s[6:7], s[4:5]
	s_andn2_b64 vcc, exec, s[6:7]
	s_mov_b64 s[6:7], -1
	v_readlane_b32 s12, v255, 28
	s_cbranch_vccz .LBB0_532
	s_and_b64 s[4:5], s[4:5], exec
	s_cselect_b32 s2, 1, 2
	s_cmp_lg_u32 s44, 0
	s_mov_b32 s4, 4
	s_cselect_b32 s2, s2, 0
	s_ashr_i32 s5, s4, 31
	s_lshl_b64 s[4:5], s[4:5], 3
	s_add_u32 s4, s0, s4
	s_mul_i32 s6, s36, 3
	s_addc_u32 s5, s1, s5
	s_add_i32 s6, s2, s6
	v_cmp_lt_i32_e32 vcc, v181, v180
	s_lshl_b32 s20, s6, 10
	s_load_dwordx2 s[4:5], s[4:5], 0x0
	v_cndmask_b32_e32 v0, v169, v181, vcc
	v_cmp_lt_i32_e32 vcc, v182, v180
	s_lshl_b64 s[6:7], s[20:21], 2
	v_lshlrev_b32_e32 v35, 2, v0
	v_cndmask_b32_e32 v0, v169, v182, vcc
	v_cmp_lt_i32_e32 vcc, v183, v180
	s_waitcnt lgkmcnt(0)
	s_add_u32 s6, s4, s6
	v_lshlrev_b32_e32 v40, 2, v0
	v_cndmask_b32_e32 v0, v169, v183, vcc
	v_cmp_lt_i32_e32 vcc, v192, v180
	s_addc_u32 s7, s5, s7
	s_lshl_b32 s4, s12, 3
	v_lshlrev_b32_e32 v41, 2, v0
	v_cndmask_b32_e32 v0, v169, v192, vcc
	v_cmp_lt_i32_e32 vcc, v254, v180
	s_add_i32 s4, s4, s50
	v_lshlrev_b32_e32 v42, 2, v0
	v_cndmask_b32_e32 v0, v169, v254, vcc
	v_cmp_lt_i32_e32 vcc, v186, v180
	s_mulk_i32 s2, 0x3000
	s_mul_i32 s4, s4, 34
	v_lshlrev_b32_e32 v43, 2, v0
	v_cndmask_b32_e32 v0, v169, v186, vcc
	s_add_u32 s2, s29, s2
	v_lshlrev_b32_e32 v44, 2, v0
	s_addc_u32 s10, s94, 0
	v_lshlrev_b32_e32 v0, 4, v194
	s_ashr_i32 s5, s4, 31
	s_add_i32 s11, s4, 33
	v_lshlrev_b32_e32 v34, 2, v194
	v_lshl_add_u64 v[36:37], s[6:7], 0, v[0:1]
	s_lshl_b64 s[6:7], s[4:5], 12
	v_or_b32_e32 v16, 0x100, v34
	v_lshlrev_b32_e32 v0, 3, v194
	s_add_u32 s6, s54, s6
	s_mul_i32 s8, s12, 0x110
	s_mul_i32 s9, s50, 34
	v_mov_b32_e32 v2, v1
	v_mov_b32_e32 v3, v1
	v_mov_b32_e32 v4, v1
	v_mov_b32_e32 v5, v1
	v_mov_b32_e32 v6, v1
	v_mov_b32_e32 v7, v1
	v_mov_b32_e32 v8, v1
	v_mov_b32_e32 v9, v1
	v_mov_b32_e32 v10, v1
	v_mov_b32_e32 v11, v1
	v_mov_b32_e32 v12, v1
	v_mov_b32_e32 v13, v1
	v_mov_b32_e32 v14, v1
	v_mov_b32_e32 v15, v1
	v_or_b32_e32 v18, 0x200, v34
	v_or_b32_e32 v20, 0x300, v34
	v_lshl_add_u64 v[38:39], s[58:59], 0, v[0:1]
	s_addc_u32 s7, s55, s7
	s_add_i32 s8, s8, s9
	v_mov_b32_e32 v0, v1
	v_lshlrev_b32_e32 v45, 2, v16
	v_mov_b64_e32 v[16:17], v[14:15]
	s_mov_b32 s17, -1
	s_add_i32 s16, s8, -1
	v_lshlrev_b32_e32 v46, 2, v18
	v_lshlrev_b32_e32 v47, 2, v20
	v_mov_b64_e32 v[14:15], v[12:13]
	v_mov_b64_e32 v[12:13], v[10:11]
	v_mov_b64_e32 v[10:11], v[8:9]
	v_mov_b64_e32 v[8:9], v[6:7]
	v_mov_b64_e32 v[6:7], v[4:5]
	v_mov_b64_e32 v[4:5], v[2:3]
	v_mov_b64_e32 v[2:3], v[0:1]
	s_mov_b32 s101, 0
	s_cmp_eq_u32 s98, 2
	s_cbranch_scc0 .Lnp_nosplit
	s_and_b32 s99, s12, 31
	s_lshr_b32 s8, s12, 5
	s_cmp_lt_u32 s99, 8
	s_cbranch_scc0 .Lnp_classB
	s_mov_b64 s[18:19], exec
	v_readlane_b32 s30, v255, 3
	v_readlane_b32 s31, v255, 4
	s_and_b64 s[30:31], s[18:19], s[30:31]
	s_mov_b64 exec, s[30:31]
	s_cbranch_execz .Lnp_wdone_a
	s_lshl_b32 s9, s100, 6

; DI void norm_phase(Frame& F, const float* srcL, const float* srcC, const float* g, const float* modl, int sub) {
;     const int gw = F.vcu * 8 + F.wave; constexpr int RPW = TT / 2048;
;     bf16_t* H = WSP(bf16_t, WS_H);
;     int cur_bi = -1; f32x4 gs[4], sh[4];
;     for (int row = gw * RPW; row < gw * RPW + RPW; ++row) {
;         const int bi = row < TL ? (row >> 12) : 16;
.Lnp_wdone_a:
	s_mov_b64 exec, s[18:19]
	s_barrier
	s_lshl_b32 s8, s12, 3
	s_add_u32 s8, s8, s50
	s_lshl_b32 s8, s8, 1
	s_add_u32 s4, s8, 0x10000
	s_add_u32 s11, s4, 1
	s_mov_b32 s5, 0
	s_sub_u32 s16, s4, 1
	s_branch .Lnp_nosplit
.Lnp_classB:
	s_mov_b32 s101, 1
	s_mul_i32 s8, s8, 24
	s_add_u32 s8, s8, s99
	s_sub_u32 s8, s8, 8
	s_lshl_b32 s8, s8, 3
	s_add_u32 s8, s8, s50
	s_lshl_b32 s9, s8, 7
	s_mul_hi_u32 s4, s9, 0xaaaaaaab
	s_lshr_b32 s4, s4, 1
	s_add_u32 s9, s9, 0x80
	s_mul_hi_u32 s11, s9, 0xaaaaaaab
	s_lshr_b32 s11, s11, 1
	s_sub_u32 s11, s11, 1
	s_mov_b32 s5, 0
	s_sub_u32 s16, s4, 1
	s_lshl_b64 s[6:7], s[4:5], 12
	s_add_u32 s6, s54, s6
	s_addc_u32 s7, s55, s7

; DI unsigned pk2(float lo, float hi) { f32x2 v = {lo, hi}; bf16x2_t b = __builtin_convertvector(v, bf16x2_t); return __builtin_bit_cast(unsigned, b); }
; DI void norm_phase(Frame& F, const float* srcL, const float* srcC, const float* g, const float* modl, int sub) {
;     ...
;     for (int row = gw * RPW; row < gw * RPW + RPW; ++row) {
;         const int bi = row < TL ? (row >> 12) : 16;
;         if (bi != cur_bi) { cur_bi = bi; const float* mp = modl + (size_t)bi * MODW + sub * 3072;
; #pragma unroll
;             for (int j = 0; j < 4; ++j) { const int k = (F.lane + 64 * j) * 4; const f32x4 gg = *(const f32x4*)(g + k), sc = *(const f32x4*)(mp + 1024 + k); sh[j] = *(const f32x4*)(mp + k); gs[j] = gg * (sc + 1.0f); } }
;         const float* src = row < TL ? srcL + (size_t)row * DM : srcC + (size_t)(row - TL) * DM;
;         f32x4 v[4]; float ss = 0.f;
; #pragma unroll
;         for (int j = 0; j < 4; ++j) { v[j] = __builtin_nontemporal_load((const f32x4*)(src + (F.lane + 64 * j) * 4)); ss += (v[j][0] * v[j][0] + v[j][1] * v[j][1]) + (v[j][2] * v[j][2] + v[j][3] * v[j][3]); }
;         const float rstd = rsqrtf(wave_sum(ss) * (1.0f / DM) + EPS);
;         bf16_t* hp = H + (size_t)row * DM;
; #pragma unroll
;         for (int j = 0; j < 4; ++j) { const f32x4 o = v[j] * rstd * gs[j] + sh[j]; u32x2 w; w.x = pk2(o[0], o[1]); w.y = pk2(o[2], o[3]); *(u32x2*)(hp + (F.lane + 64 * j) * 4) = w; }
;     }
.LBB0_531:
	s_cmp_eq_u32 s101, 1
	s_cbranch_scc0 .Lnp_fin
	s_mov_b32 s101, 0
	s_mov_b64 s[18:19], exec
	v_readlane_b32 s30, v255, 3
	v_readlane_b32 s31, v255, 4
	s_and_b64 s[30:31], s[18:19], s[30:31]
	s_mov_b64 exec, s[30:31]
	s_cbranch_execz .Lnp_wdone_b
	s_lshl_b32 s9, s100, 6

; DI void norm_pair_phase(Frame& F, const float* srcL, const float* srcC, const float* g, const float* modl, int sub) {
;     bf16_t* H = WSP(bf16_t, WS_H); bf16_t* HS = WSP(bf16_t, WS_HS);
;     const int gw = F.vcu * 8 + F.wave, NGW = F.G * 8, lane = F.lane;
;     int cur_bi = -1; f32x4 gs[4], sh[4];
;     const int NT_L = NB * 2049, NT = NT_L + TC / 2;
;     for (int task = gw; task < NT; task += NGW) {
;         int bi, r1, r2, j; bool single, isc = task >= NT_L;
;         if (!isc) { bi = task / 2049; j = task % 2049; single = (j == 0 || j == 2048); r1 = bi * SEQ + j; r2 = single ? r1 : bi * SEQ + SEQ - j; }
;         else { bi = 16; j = 0; single = false; r1 = TL + 2 * (task - NT_L); r2 = r1 + 1; }
;         if (bi != cur_bi) { cur_bi = bi; const float* mp = modl + (size_t)bi * MODW + sub * 3072;
; #pragma unroll
;             for (int q = 0; q < 4; ++q) { const int k = (lane + 64 * q) * 4; const f32x4 gg = *(const f32x4*)(g + k), sc = *(const f32x4*)(mp + 1024 + k); sh[q] = *(const f32x4*)(mp + k); gs[q] = gg * (sc + 1.0f); } }
.LBB0_532:
	s_and_b64 vcc, exec, s[6:7]
	s_cbranch_vccz .LBB0_578
	s_mov_b32 s4, 4
	s_ashr_i32 s5, s4, 31
	s_lshl_b64 s[4:5], s[4:5], 3
	s_add_u32 s4, s0, s4
	s_addc_u32 s5, s1, s5
	s_lshl_b32 s2, s12, 3
	s_add_i32 s2, s2, s50
	s_load_dwordx2 s[4:5], s[4:5], 0x0
	s_cmp_gt_i32 s2, 0x880f
	s_waitcnt lgkmcnt(0)
	s_cbranch_scc1 .LBB0_578
	s_add_u32 s60, s60, 0x36d00000
	s_addc_u32 s61, s61, 0
	s_lshl_b32 s10, s3, 3
	v_readlane_b32 s6, v255, 52
	v_readlane_b32 s7, v255, 53
	s_add_u32 s4, s4, s6
	s_addc_u32 s5, s5, s7
	v_lshlrev_b32_e32 v0, 4, v194
	v_cmp_lt_i32_e32 vcc, v181, v180
	v_lshl_add_u64 v[68:69], s[4:5], 0, v[0:1]
	v_lshlrev_b32_e32 v66, 2, v194
	v_cndmask_b32_e32 v0, v169, v181, vcc
	v_cmp_lt_i32_e32 vcc, v182, v180
	v_lshlrev_b32_e32 v67, 2, v0
	v_or_b32_e32 v2, 0x100, v66
	v_cndmask_b32_e32 v0, v169, v182, vcc
	v_cmp_lt_i32_e32 vcc, v183, v180
	v_lshlrev_b32_e32 v92, 2, v0
	v_or_b32_e32 v4, 0x200, v66
	v_cndmask_b32_e32 v0, v169, v183, vcc
	v_cmp_lt_i32_e32 vcc, v192, v180
	v_lshlrev_b32_e32 v93, 2, v0
	s_add_u32 s11, s29, 0x3000
	v_cndmask_b32_e32 v0, v169, v192, vcc
	v_cmp_lt_i32_e32 vcc, v254, v180
	v_lshlrev_b32_e32 v94, 2, v0
	v_or_b32_e32 v6, 0x300, v66
	v_cndmask_b32_e32 v0, v169, v254, vcc
	v_cmp_lt_i32_e32 vcc, v186, v180
	v_lshlrev_b32_e32 v95, 2, v0
	s_addc_u32 s16, s94, 0
	v_cndmask_b32_e32 v0, v169, v186, vcc
	v_lshlrev_b32_e32 v96, 2, v0
	v_lshlrev_b32_e32 v0, 3, v194
	v_lshl_add_u64 v[70:71], s[60:61], 0, v[0:1]
	v_lshl_add_u64 v[72:73], s[58:59], 0, v[0:1]
	v_lshlrev_b32_e32 v0, 1, v2
	v_lshl_add_u64 v[74:75], s[60:61], 0, v[0:1]
	v_lshlrev_b32_e32 v0, 1, v4
	v_lshl_add_u64 v[76:77], s[60:61], 0, v[0:1]
	v_lshlrev_b32_e32 v0, 1, v6
	s_lshl_b32 s4, s2, 1
	s_mov_b32 s19, -1
	v_lshl_add_u64 v[78:79], s[60:61], 0, v[0:1]
	s_sub_i32 s17, 0x1000, s2
	s_sub_i32 s18, s4, 31
	s_lshl_b32 s3, s3, 4
	v_lshlrev_b32_e32 v0, 2, v2
	v_lshlrev_b32_e32 v97, 2, v4
	v_lshlrev_b32_e32 v98, 2, v6
	s_mov_b32 s101, 0x880f
	s_mov_b32 s99, 0
	s_cmp_eq_u32 s98, 2
	s_cbranch_scc0 .Lpn_nosplit
	s_and_b32 s4, s12, 31
	s_lshr_b32 s5, s12, 5
	s_cmp_lt_u32 s4, 8
	s_cbranch_scc0 .Lpn_classB
	s_mov_b64 s[6:7], exec
	v_readlane_b32 s8, v255, 3
	v_readlane_b32 s9, v255, 4
	s_and_b64 s[8:9], s[6:7], s[8:9]
	s_mov_b64 exec, s[8:9]
	s_cbranch_execz .Lpn_wdone_a
	s_lshl_b32 s5, s100, 6

; DI void norm_pair_phase(Frame& F, const float* srcL, const float* srcC, const float* g, const float* modl, int sub) {
;     ...
;     const int NT_L = NB * 2049, NT = NT_L + TC / 2;
;     for (int task = gw; task < NT; task += NGW) {
;         int bi, r1, r2, j; bool single, isc = task >= NT_L;
;         if (!isc) { bi = task / 2049; j = task % 2049; single = (j == 0 || j == 2048); r1 = bi * SEQ + j; r2 = single ? r1 : bi * SEQ + SEQ - j; }
;         else { bi = 16; j = 0; single = false; r1 = TL + 2 * (task - NT_L); r2 = r1 + 1; }
.Lpn_wdone_a:
	s_mov_b64 exec, s[6:7]
	s_barrier
	s_lshl_b32 s4, s12, 3
	s_add_u32 s4, s4, s50
	s_add_u32 s2, s4, 0x8010
	s_movk_i32 s10, 0x1000
	s_mov_b32 s101, 0x880f
	s_lshl_b32 s3, s10, 1
	s_sub_i32 s17, 0x1000, s2
	s_lshl_b32 s4, s2, 1
	s_sub_i32 s18, s4, 31
	s_branch .Lpn_nosplit
.Lpn_classB:
	s_mul_i32 s5, s5, 24
	s_add_u32 s4, s4, s5
	s_sub_u32 s4, s4, 8
	s_lshl_b32 s4, s4, 3
	s_add_u32 s2, s4, s50
	s_movk_i32 s10, 0x600
	s_mov_b32 s101, 0x800f
	s_mov_b32 s99, 1
	s_lshl_b32 s3, s10, 1
	s_sub_i32 s17, 0x1000, s2
	s_lshl_b32 s4, s2, 1
	s_sub_i32 s18, s4, 31

; DI void norm_pair_phase(Frame& F, const float* srcL, const float* srcC, const float* g, const float* modl, int sub) {
;     ...
;     for (int task = gw; task < NT; task += NGW) {
;         int bi, r1, r2, j; bool single, isc = task >= NT_L;
;         if (!isc) { bi = task / 2049; j = task % 2049; single = (j == 0 || j == 2048); r1 = bi * SEQ + j; r2 = single ? r1 : bi * SEQ + SEQ - j; }
;         else { bi = 16; j = 0; single = false; r1 = TL + 2 * (task - NT_L); r2 = r1 + 1; }
.Lpn_tail:
	s_cmp_eq_u32 s99, 1
	s_cbranch_scc0 .LBB0_578
	s_mov_b32 s99, 0
	s_mov_b64 s[6:7], exec
	v_readlane_b32 s8, v255, 3
	v_readlane_b32 s9, v255, 4
	s_and_b64 s[8:9], s[6:7], s[8:9]
	s_mov_b64 exec, s[8:9]
	s_cbranch_execz .Lpn_wdone_b
	s_lshl_b32 s5, s100, 6
